# MLA loop and NA context tiles: row-max shuffles (xor 16 / xor 32) via v_permlane16/32_swap instead of ds_bpermute + lgkmcnt(0) round trips; dead shuffle-index math removed
# speedup vs baseline: 1.0192x; 1.0032x over previous
.LBB0_379:
	v_mov_b32_e32 v98, v152
	s_nop 1
	v_permlane16_swap_b32_e32 v98, v152
	v_max_f32_e32 v98, v98, v98
	v_max_f32_e32 v99, v152, v152
	v_max_f32_e32 v98, v99, v98
	v_mov_b32_e32 v99, v98
	s_nop 1
	v_permlane32_swap_b32_e32 v99, v98
	v_max_f32_e32 v99, v99, v99
	v_max_f32_e32 v98, v98, v99
	v_add_f32_e32 v99, 0x41000000, v144
	v_cmp_gt_f32_e32 vcc, v98, v99
	s_cbranch_vccz .LBB0_381
	v_max_f32_e32 v98, v98, v98
	v_max_f32_e32 v99, v144, v144
	v_max_f32_e32 v99, v99, v98
	v_sub_f32_e32 v98, v144, v99
	v_exp_f32_e32 v98, v98
	v_mov_b32_e32 v144, v99
	v_mul_f32_e32 v140, v140, v98
	v_pk_mul_f32 v[20:21], v[20:21], v[98:99] op_sel_hi:[1,0]
	v_pk_mul_f32 v[18:19], v[18:19], v[98:99] op_sel_hi:[1,0]
	v_pk_mul_f32 v[24:25], v[24:25], v[98:99] op_sel_hi:[1,0]
	v_pk_mul_f32 v[22:23], v[22:23], v[98:99] op_sel_hi:[1,0]
	v_pk_mul_f32 v[12:13], v[12:13], v[98:99] op_sel_hi:[1,0]
	v_pk_mul_f32 v[10:11], v[10:11], v[98:99] op_sel_hi:[1,0]
	v_pk_mul_f32 v[4:5], v[4:5], v[98:99] op_sel_hi:[1,0]
	v_pk_mul_f32 v[2:3], v[2:3], v[98:99] op_sel_hi:[1,0]

.LBB0_417:
	v_mov_b32_e32 v82, v152
	s_nop 1
	v_permlane16_swap_b32_e32 v82, v152
	v_max_f32_e32 v83, v152, v152
	v_max_f32_e32 v82, v82, v82
	v_max_f32_e32 v82, v83, v82
	v_mov_b32_e32 v83, v82
	s_nop 1
	v_permlane32_swap_b32_e32 v83, v82
	v_max_f32_e32 v83, v83, v83
	v_max_f32_e32 v82, v82, v83
	v_add_f32_e32 v83, 0x41000000, v142
	v_cmp_gt_f32_e32 vcc, v82, v83
	s_cbranch_vccz .LBB0_336
	v_max_f32_e32 v82, v82, v82
	v_max_f32_e32 v83, v142, v142
	v_max_f32_e32 v83, v83, v82
	v_sub_f32_e32 v82, v142, v83
	v_exp_f32_e32 v82, v82
	v_mov_b32_e32 v142, v83
	v_mul_f32_e32 v137, v137, v82
	v_pk_mul_f32 v[32:33], v[32:33], v[82:83] op_sel_hi:[1,0]
	v_pk_mul_f32 v[30:31], v[30:31], v[82:83] op_sel_hi:[1,0]
	v_pk_mul_f32 v[28:29], v[28:29], v[82:83] op_sel_hi:[1,0]
	v_pk_mul_f32 v[26:27], v[26:27], v[82:83] op_sel_hi:[1,0]
	v_pk_mul_f32 v[16:17], v[16:17], v[82:83] op_sel_hi:[1,0]
	v_pk_mul_f32 v[14:15], v[14:15], v[82:83] op_sel_hi:[1,0]
	v_pk_mul_f32 v[8:9], v[8:9], v[82:83] op_sel_hi:[1,0]
	v_pk_mul_f32 v[6:7], v[6:7], v[82:83] op_sel_hi:[1,0]
	s_branch .LBB0_336

.LBB0_559:
	s_and_b32 s5, s4, 0x80
	v_or_b32_e32 v142, s5, v125
	v_mad_u32_u24 v143, v142, s12, v0
	ds_read_b128 v[78:81], v143
	ds_read_b128 v[82:85], v143 offset:64
	ds_read_b128 v[86:89], v143 offset:128
	ds_read_b128 v[94:97], v143 offset:3328
	ds_read_b128 v[98:101], v143 offset:3392
	ds_read_b128 v[144:147], v143 offset:3456
	s_setprio 1
	s_waitcnt lgkmcnt(5)
	v_mfma_f32_16x16x32_bf16 v[90:93], v[78:81], v[2:5], 0
	v_mfma_f32_16x16x32_bf16 v[78:81], v[78:81], v[26:29], 0
	s_waitcnt lgkmcnt(4)
	v_mfma_f32_16x16x32_bf16 v[90:93], v[82:85], v[6:9], v[90:93]
	v_mfma_f32_16x16x32_bf16 v[78:81], v[82:85], v[30:33], v[78:81]
	s_waitcnt lgkmcnt(3)
	v_mfma_f32_16x16x32_bf16 v[106:109], v[86:89], v[38:41], v[90:93]
	v_mfma_f32_16x16x32_bf16 v[90:93], v[86:89], v[42:45], v[78:81]
	s_waitcnt lgkmcnt(2)
	v_mfma_f32_16x16x32_bf16 v[78:81], v[94:97], v[2:5], 0
	v_mfma_f32_16x16x32_bf16 v[82:85], v[94:97], v[26:29], 0
	s_waitcnt lgkmcnt(1)
	v_mfma_f32_16x16x32_bf16 v[78:81], v[98:101], v[6:9], v[78:81]
	v_mfma_f32_16x16x32_bf16 v[82:85], v[98:101], v[30:33], v[82:85]
	s_waitcnt lgkmcnt(0)
	v_mfma_f32_16x16x32_bf16 v[102:105], v[144:147], v[38:41], v[78:81]
	v_mfma_f32_16x16x32_bf16 v[82:85], v[144:147], v[42:45], v[82:85]
	s_setprio 0
	s_nop 2
	ds_read_b128 v[78:81], v143 offset:6656
	ds_read_b128 v[86:89], v143 offset:6720
	ds_read_b128 v[94:97], v143 offset:6784
	ds_read_b128 v[144:147], v143 offset:9984
	ds_read_b128 v[148:151], v143 offset:10048
	ds_read_b128 v[152:155], v143 offset:10112
	s_setprio 1
	s_waitcnt lgkmcnt(5)
	v_mfma_f32_16x16x32_bf16 v[98:101], v[78:81], v[2:5], 0
	v_mfma_f32_16x16x32_bf16 v[78:81], v[78:81], v[26:29], 0
	s_waitcnt lgkmcnt(4)
	v_mfma_f32_16x16x32_bf16 v[98:101], v[86:89], v[6:9], v[98:101]
	v_mfma_f32_16x16x32_bf16 v[78:81], v[86:89], v[30:33], v[78:81]
	s_waitcnt lgkmcnt(3)
	v_mfma_f32_16x16x32_bf16 v[98:101], v[94:97], v[38:41], v[98:101]
	v_mfma_f32_16x16x32_bf16 v[86:89], v[94:97], v[42:45], v[78:81]
	s_waitcnt lgkmcnt(2)
	v_mfma_f32_16x16x32_bf16 v[78:81], v[144:147], v[2:5], 0
	v_mfma_f32_16x16x32_bf16 v[94:97], v[144:147], v[26:29], 0
	s_waitcnt lgkmcnt(1)
	v_mfma_f32_16x16x32_bf16 v[78:81], v[148:151], v[6:9], v[78:81]
	v_mfma_f32_16x16x32_bf16 v[144:147], v[148:151], v[30:33], v[94:97]
	s_waitcnt lgkmcnt(0)
	v_mfma_f32_16x16x32_bf16 v[94:97], v[152:155], v[38:41], v[78:81]
	v_mfma_f32_16x16x32_bf16 v[78:81], v[152:155], v[42:45], v[144:147]
	s_setprio 0
	v_max3_f32 v143, v106, s18, v107
	v_max3_f32 v143, v143, v108, v109
	v_max3_f32 v143, v143, v102, v103
	v_max3_f32 v143, v143, v104, v105
	v_max3_f32 v143, v143, v98, v99
	v_max3_f32 v143, v143, v100, v101
	v_max3_f32 v143, v143, v94, v95
	v_max3_f32 v143, v143, v96, v97
	v_mul_f32_e32 v143, 0x3e16c740, v143
	v_mov_b32_e32 v144, v143
	s_nop 1
	v_permlane16_swap_b32_e32 v144, v143
	v_max_f32_e32 v143, v143, v144
	v_mov_b32_e32 v144, v143
	s_nop 1
	v_permlane32_swap_b32_e32 v144, v143
	v_max_f32_e32 v143, v143, v144
	v_add_f32_e32 v144, 0x41000000, v139
	v_cmp_gt_f32_e32 vcc, v143, v144
	s_cbranch_vccz .LBB0_561
	v_max_f32_e32 v143, v143, v143
	v_max_f32_e32 v144, v139, v139
	v_max_f32_e32 v143, v144, v143
	v_sub_f32_e32 v139, v139, v143
	v_exp_f32_e32 v144, v139
	v_mov_b32_e32 v139, v143
	v_mul_f32_e32 v141, v141, v144
	v_pk_mul_f32 v[76:77], v[76:77], v[144:145] op_sel_hi:[1,0]
	v_pk_mul_f32 v[74:75], v[74:75], v[144:145] op_sel_hi:[1,0]
	v_pk_mul_f32 v[72:73], v[72:73], v[144:145] op_sel_hi:[1,0]
	v_pk_mul_f32 v[70:71], v[70:71], v[144:145] op_sel_hi:[1,0]
	v_pk_mul_f32 v[68:69], v[68:69], v[144:145] op_sel_hi:[1,0]
	v_pk_mul_f32 v[66:67], v[66:67], v[144:145] op_sel_hi:[1,0]
	v_pk_mul_f32 v[64:65], v[64:65], v[144:145] op_sel_hi:[1,0]
	v_pk_mul_f32 v[62:63], v[62:63], v[144:145] op_sel_hi:[1,0]
.LBB0_561:
	v_max3_f32 v143, v90, s18, v91
	v_max3_f32 v143, v143, v92, v93
	v_max3_f32 v143, v143, v82, v83
	v_max3_f32 v143, v143, v84, v85
	v_max3_f32 v143, v143, v86, v87
	v_max3_f32 v143, v143, v88, v89
	v_max3_f32 v143, v143, v78, v79
	v_max3_f32 v143, v143, v80, v81
	v_mul_f32_e32 v143, 0x3e16c740, v143
	v_mov_b32_e32 v144, v143
	s_nop 1
	v_permlane16_swap_b32_e32 v144, v143
	v_max_f32_e32 v143, v143, v144
	v_mov_b32_e32 v144, v143
	s_nop 1
	v_permlane32_swap_b32_e32 v144, v143
	v_max_f32_e32 v143, v143, v144
	v_add_f32_e32 v144, 0x41000000, v138
	v_cmp_gt_f32_e32 vcc, v143, v144
	s_cbranch_vccz .LBB0_563
	v_max_f32_e32 v143, v143, v143
	v_max_f32_e32 v144, v138, v138
	v_max_f32_e32 v143, v144, v143
	v_sub_f32_e32 v138, v138, v143
	v_exp_f32_e32 v138, v138
	s_nop 0
	v_mul_f32_e32 v140, v140, v138
	v_pk_mul_f32 v[60:61], v[60:61], v[138:139] op_sel_hi:[1,0]
	v_pk_mul_f32 v[58:59], v[58:59], v[138:139] op_sel_hi:[1,0]
	v_pk_mul_f32 v[56:57], v[56:57], v[138:139] op_sel_hi:[1,0]
	v_pk_mul_f32 v[54:55], v[54:55], v[138:139] op_sel_hi:[1,0]
	v_pk_mul_f32 v[52:53], v[52:53], v[138:139] op_sel_hi:[1,0]
	v_pk_mul_f32 v[50:51], v[50:51], v[138:139] op_sel_hi:[1,0]
	v_pk_mul_f32 v[48:49], v[48:49], v[138:139] op_sel_hi:[1,0]
	v_pk_mul_f32 v[46:47], v[46:47], v[138:139] op_sel_hi:[1,0]
	v_mov_b32_e32 v138, v143
.LBB0_563:
	v_fma_f32 v106, v106, s21, -v139
	v_exp_f32_e32 v106, v106
	v_fma_f32 v107, v107, s21, -v139
	v_exp_f32_e32 v107, v107
	v_fma_f32 v108, v108, s21, -v139
	v_exp_f32_e32 v108, v108
	v_fma_f32 v109, v109, s21, -v139
	v_exp_f32_e32 v109, v109
	v_fma_f32 v102, v102, s21, -v139
	v_mul_u32_u24_e32 v160, 0xd0, v142
	v_add_f32_e32 v142, 0, v106
	v_exp_f32_e32 v102, v102
	v_fma_f32 v103, v103, s21, -v139
	v_add_f32_e32 v142, v107, v142
	v_exp_f32_e32 v103, v103
	v_fma_f32 v104, v104, s21, -v139
	v_add_f32_e32 v142, v108, v142
	v_exp_f32_e32 v104, v104
	v_fma_f32 v105, v105, s21, -v139
	v_add_f32_e32 v142, v109, v142
	v_exp_f32_e32 v105, v105
	v_fma_f32 v98, v98, s21, -v139
	v_cvt_pk_bf16_f32 v106, v106, v107
	v_cvt_pk_bf16_f32 v107, v108, v109
	v_add_f32_e32 v108, v102, v142
	v_exp_f32_e32 v98, v98
	v_fma_f32 v99, v99, s21, -v139
	v_add_f32_e32 v108, v103, v108
	v_exp_f32_e32 v99, v99
	v_fma_f32 v100, v100, s21, -v139
	v_add_f32_e32 v108, v104, v108
	v_exp_f32_e32 v100, v100
	v_fma_f32 v101, v101, s21, -v139
	v_add_f32_e32 v142, v105, v108
	v_exp_f32_e32 v101, v101
	v_fma_f32 v94, v94, s21, -v139
	v_cvt_pk_bf16_f32 v108, v102, v103
	v_add_f32_e32 v102, v98, v142
	v_exp_f32_e32 v94, v94
	v_fma_f32 v95, v95, s21, -v139
	v_add_f32_e32 v102, v99, v102
	v_exp_f32_e32 v95, v95
	v_fma_f32 v96, v96, s21, -v139
	v_add_f32_e32 v102, v100, v102
	v_exp_f32_e32 v96, v96
	v_fma_f32 v97, v97, s21, -v139
	v_add_f32_e32 v102, v101, v102
	v_exp_f32_e32 v97, v97
	v_cvt_pk_bf16_f32 v98, v98, v99
	v_cvt_pk_bf16_f32 v99, v100, v101
	v_add_f32_e32 v100, v94, v102
	v_add_f32_e32 v100, v95, v100
	v_add_f32_e32 v100, v96, v100
	v_fma_f32 v90, v90, s21, -v138
	v_fma_f32 v86, v86, s21, -v138
	v_fma_f32 v78, v78, s21, -v138
	v_add_f32_e32 v102, v97, v100
	v_cvt_pk_bf16_f32 v100, v94, v95
	v_or_b32_e32 v94, s5, v132
	v_exp_f32_e32 v144, v90
	v_fma_f32 v90, v91, s21, -v138
	v_exp_f32_e32 v159, v86
	v_fma_f32 v86, v87, s21, -v138
	v_exp_f32_e32 v154, v78
	v_fma_f32 v78, v79, s21, -v138
	v_exp_f32_e32 v145, v90
	v_fma_f32 v90, v92, s21, -v138
	v_exp_f32_e32 v146, v86
	v_fma_f32 v86, v88, s21, -v138
	v_exp_f32_e32 v151, v78
	v_fma_f32 v78, v80, s21, -v138
	v_mul_u32_u24_e32 v143, 0x48, v94
	v_exp_f32_e32 v147, v90
	v_fma_f32 v90, v93, s21, -v138
	v_exp_f32_e32 v148, v86
	v_fma_f32 v86, v89, s21, -v138
	v_exp_f32_e32 v152, v78
	v_fma_f32 v78, v81, s21, -v138
	v_lshl_add_u32 v142, v143, 1, v130
	v_cvt_pk_bf16_f32 v101, v96, v97
	v_exp_f32_e32 v149, v90
	v_exp_f32_e32 v150, v86
	v_exp_f32_e32 v155, v78
	ds_read_b64_tr_b16 v[80:81], v142 offset:55552
	ds_read_b64_tr_b16 v[78:79], v142 offset:53248
	ds_read_b64_tr_b16 v[88:89], v142 offset:55584
	ds_read_b64_tr_b16 v[86:87], v142 offset:53280
	ds_read_b64_tr_b16 v[90:91], v142 offset:57856
	ds_read_b64_tr_b16 v[92:93], v142 offset:60160
	ds_read_b64_tr_b16 v[96:97], v142 offset:60192
	ds_read_b64_tr_b16 v[94:95], v142 offset:57888
	v_fma_f32 v82, v82, s21, -v138
	v_exp_f32_e32 v153, v82
	v_fma_f32 v82, v83, s21, -v138
	v_exp_f32_e32 v156, v82
	v_fma_f32 v82, v84, s21, -v138
	v_exp_f32_e32 v157, v82
	v_fma_f32 v82, v85, s21, -v138
	v_exp_f32_e32 v158, v82
	v_cvt_pk_bf16_f32 v109, v104, v105
	v_add_f32_e32 v141, v141, v102
	v_cvt_pk_bf16_f32 v82, v144, v145
	v_cvt_pk_bf16_f32 v83, v147, v149
	v_cvt_pk_bf16_f32 v84, v153, v156
	v_cvt_pk_bf16_f32 v85, v157, v158
	v_cvt_pk_bf16_f32 v102, v159, v146
	v_cvt_pk_bf16_f32 v103, v148, v150
	v_cvt_pk_bf16_f32 v104, v154, v151
	v_cvt_pk_bf16_f32 v105, v152, v155
	s_setprio 1
	s_waitcnt lgkmcnt(6)
	v_mfma_f32_16x16x32_bf16 v[74:77], v[78:81], v[106:109], v[74:77]
	v_mfma_f32_16x16x32_bf16 v[58:61], v[78:81], v[82:85], v[58:61]
	s_waitcnt lgkmcnt(4)
	v_mfma_f32_16x16x32_bf16 v[70:73], v[86:89], v[106:109], v[70:73]
	v_mfma_f32_16x16x32_bf16 v[78:81], v[86:89], v[82:85], v[54:57]
	s_waitcnt lgkmcnt(2)
	v_mfma_f32_16x16x32_bf16 v[74:77], v[90:93], v[98:101], v[74:77]
	v_mfma_f32_16x16x32_bf16 v[58:61], v[90:93], v[102:105], v[58:61]
	s_waitcnt lgkmcnt(0)
	v_mfma_f32_16x16x32_bf16 v[54:57], v[94:97], v[98:101], v[70:73]
	v_mfma_f32_16x16x32_bf16 v[70:73], v[94:97], v[102:105], v[78:81]
	s_setprio 0
	s_nop 1
	ds_read_b64_tr_b16 v[80:81], v142 offset:55616
	ds_read_b64_tr_b16 v[78:79], v142 offset:53312
	ds_read_b64_tr_b16 v[88:89], v142 offset:55648
	ds_read_b64_tr_b16 v[86:87], v142 offset:53344
	ds_read_b64_tr_b16 v[90:91], v142 offset:57920
	ds_read_b64_tr_b16 v[92:93], v142 offset:60224
	ds_read_b64_tr_b16 v[96:97], v142 offset:60256
	ds_read_b64_tr_b16 v[94:95], v142 offset:57952
	s_setprio 1
	s_waitcnt lgkmcnt(6)
	v_mfma_f32_16x16x32_bf16 v[66:69], v[78:81], v[106:109], v[66:69]
	v_mfma_f32_16x16x32_bf16 v[78:81], v[78:81], v[82:85], v[50:53]
	s_waitcnt lgkmcnt(2)
	v_mfma_f32_16x16x32_bf16 v[50:53], v[90:93], v[98:101], v[66:69]
	v_mfma_f32_16x16x32_bf16 v[66:69], v[90:93], v[102:105], v[78:81]
	v_mfma_f32_16x16x32_bf16 v[62:65], v[86:89], v[106:109], v[62:65]
	v_mfma_f32_16x16x32_bf16 v[78:81], v[86:89], v[82:85], v[46:49]
	s_waitcnt lgkmcnt(0)
	v_mfma_f32_16x16x32_bf16 v[46:49], v[94:97], v[98:101], v[62:65]
	v_mfma_f32_16x16x32_bf16 v[62:65], v[94:97], v[102:105], v[78:81]
	s_setprio 0
	v_add_u32_e32 v160, v0, v160
	s_nop 2
	ds_read_b128 v[78:81], v160 offset:13312
	ds_read_b128 v[82:85], v160 offset:13376
	ds_read_b128 v[86:89], v160 offset:13440
	ds_read_b128 v[94:97], v160 offset:16640
	ds_read_b128 v[98:101], v160 offset:16704
	ds_read_b128 v[102:105], v160 offset:16768
	s_setprio 1
	s_waitcnt lgkmcnt(5)
	v_mfma_f32_16x16x32_bf16 v[90:93], v[78:81], v[2:5], 0
	v_mfma_f32_16x16x32_bf16 v[78:81], v[78:81], v[26:29], 0
	s_waitcnt lgkmcnt(4)
	v_mfma_f32_16x16x32_bf16 v[90:93], v[82:85], v[6:9], v[90:93]
	v_mfma_f32_16x16x32_bf16 v[78:81], v[82:85], v[30:33], v[78:81]
	s_waitcnt lgkmcnt(3)
	v_mfma_f32_16x16x32_bf16 v[106:109], v[86:89], v[38:41], v[90:93]
	v_mfma_f32_16x16x32_bf16 v[90:93], v[86:89], v[42:45], v[78:81]
	s_waitcnt lgkmcnt(2)
	v_mfma_f32_16x16x32_bf16 v[78:81], v[94:97], v[2:5], 0
	v_mfma_f32_16x16x32_bf16 v[82:85], v[94:97], v[26:29], 0
	s_waitcnt lgkmcnt(1)
	v_mfma_f32_16x16x32_bf16 v[78:81], v[98:101], v[6:9], v[78:81]
	v_mfma_f32_16x16x32_bf16 v[82:85], v[98:101], v[30:33], v[82:85]
	s_waitcnt lgkmcnt(0)
	v_mfma_f32_16x16x32_bf16 v[98:101], v[102:105], v[38:41], v[78:81]
	v_mfma_f32_16x16x32_bf16 v[82:85], v[102:105], v[42:45], v[82:85]
	s_setprio 0
	s_nop 2
	ds_read_b128 v[78:81], v160 offset:19968
	ds_read_b128 v[86:89], v160 offset:20032
	ds_read_b128 v[94:97], v160 offset:20096
	ds_read_b128 v[164:167], v160 offset:23296
	ds_read_b128 v[168:171], v160 offset:23360
	ds_read_b128 v[172:175], v160 offset:23424
	s_setprio 1
	s_waitcnt lgkmcnt(5)
	v_mfma_f32_16x16x32_bf16 v[102:105], v[78:81], v[2:5], 0
	v_mfma_f32_16x16x32_bf16 v[78:81], v[78:81], v[26:29], 0
	s_waitcnt lgkmcnt(4)
	v_mfma_f32_16x16x32_bf16 v[102:105], v[86:89], v[6:9], v[102:105]
	v_mfma_f32_16x16x32_bf16 v[78:81], v[86:89], v[30:33], v[78:81]
	s_waitcnt lgkmcnt(3)
	v_mfma_f32_16x16x32_bf16 v[102:105], v[94:97], v[38:41], v[102:105]
	v_mfma_f32_16x16x32_bf16 v[86:89], v[94:97], v[42:45], v[78:81]
	s_waitcnt lgkmcnt(2)
	v_mfma_f32_16x16x32_bf16 v[78:81], v[164:167], v[2:5], 0
	v_mfma_f32_16x16x32_bf16 v[94:97], v[164:167], v[26:29], 0
	s_waitcnt lgkmcnt(1)
	v_mfma_f32_16x16x32_bf16 v[78:81], v[168:171], v[6:9], v[78:81]
	v_mfma_f32_16x16x32_bf16 v[164:167], v[168:171], v[30:33], v[94:97]
	s_waitcnt lgkmcnt(0)
	v_mfma_f32_16x16x32_bf16 v[94:97], v[172:175], v[38:41], v[78:81]
	v_mfma_f32_16x16x32_bf16 v[78:81], v[172:175], v[42:45], v[164:167]
	s_setprio 0
	v_max3_f32 v160, v106, s18, v107
	v_max3_f32 v160, v160, v108, v109
	v_max3_f32 v160, v160, v98, v99
	v_max3_f32 v160, v160, v100, v101
	v_max3_f32 v160, v160, v102, v103
	v_max3_f32 v160, v160, v104, v105
	v_max3_f32 v160, v160, v94, v95
	v_max3_f32 v160, v160, v96, v97
	v_mul_f32_e32 v160, 0x3e16c740, v160
	v_mov_b32_e32 v161, v160
	s_nop 1
	v_permlane16_swap_b32_e32 v161, v160
	v_max_f32_e32 v160, v160, v161
	v_mov_b32_e32 v161, v160
	s_nop 1
	v_permlane32_swap_b32_e32 v161, v160
	v_max_f32_e32 v160, v160, v161
	v_add_f32_e32 v161, 0x41000000, v139
	v_cmp_gt_f32_e32 vcc, v160, v161
	s_cbranch_vccz .LBB0_565
	v_max_f32_e32 v160, v160, v160
	v_max_f32_e32 v161, v139, v139
	v_max_f32_e32 v161, v161, v160
	v_sub_f32_e32 v139, v139, v161
	v_exp_f32_e32 v160, v139
	v_mov_b32_e32 v139, v161
	v_mul_f32_e32 v141, v141, v160
	v_pk_mul_f32 v[76:77], v[76:77], v[160:161] op_sel_hi:[1,0]
	v_pk_mul_f32 v[74:75], v[74:75], v[160:161] op_sel_hi:[1,0]
	v_pk_mul_f32 v[56:57], v[56:57], v[160:161] op_sel_hi:[1,0]
	v_pk_mul_f32 v[54:55], v[54:55], v[160:161] op_sel_hi:[1,0]
	v_pk_mul_f32 v[52:53], v[52:53], v[160:161] op_sel_hi:[1,0]
	v_pk_mul_f32 v[50:51], v[50:51], v[160:161] op_sel_hi:[1,0]
	v_pk_mul_f32 v[48:49], v[48:49], v[160:161] op_sel_hi:[1,0]
	v_pk_mul_f32 v[46:47], v[46:47], v[160:161] op_sel_hi:[1,0]
	v_xor_b32_e32 v160, 0x80000000, v161
	s_branch .LBB0_566

.LBB0_566:
	v_add_f32_e32 v144, 0, v144
	v_add_f32_e32 v144, v145, v144
	v_max3_f32 v145, v90, s18, v91
	v_max3_f32 v145, v145, v92, v93
	v_max3_f32 v145, v145, v82, v83
	v_max3_f32 v145, v145, v84, v85
	v_max3_f32 v145, v145, v86, v87
	v_max3_f32 v145, v145, v88, v89
	v_max3_f32 v145, v145, v78, v79
	v_add_f32_e32 v144, v147, v144
	v_max3_f32 v145, v145, v80, v81
	v_add_f32_e32 v144, v149, v144
	v_mul_f32_e32 v145, 0x3e16c740, v145
	v_add_f32_e32 v144, v153, v144
	v_mov_b32_e32 v147, v145
	s_nop 1
	v_permlane16_swap_b32_e32 v147, v145
	v_add_f32_e32 v144, v156, v144
	v_add_f32_e32 v144, v157, v144
	v_add_f32_e32 v144, v158, v144
	v_add_f32_e32 v144, v159, v144
	v_add_f32_e32 v144, v146, v144
	v_max_f32_e32 v146, v147, v147
	v_add_f32_e32 v144, v148, v144
	v_max_f32_e32 v145, v145, v146
	v_add_f32_e32 v144, v150, v144
	v_mov_b32_e32 v146, v145
	s_nop 1
	v_permlane32_swap_b32_e32 v146, v145
	v_add_f32_e32 v144, v154, v144
	v_add_f32_e32 v144, v151, v144
	v_add_f32_e32 v144, v152, v144
	v_add_f32_e32 v144, v155, v144
	v_add_f32_e32 v140, v140, v144
	v_max_f32_e32 v144, v146, v146
	v_max_f32_e32 v144, v145, v144
	v_add_f32_e32 v145, 0x41000000, v138
	v_cmp_gt_f32_e32 vcc, v144, v145
	s_cbranch_vccz .LBB0_568
	v_max_f32_e32 v144, v144, v144
	v_max_f32_e32 v145, v138, v138
	v_max_f32_e32 v145, v145, v144
	v_sub_f32_e32 v138, v138, v145
	v_exp_f32_e32 v138, v138
	v_xor_b32_e32 v144, 0x80000000, v145
	v_mul_f32_e32 v140, v140, v138
	v_pk_mul_f32 v[60:61], v[60:61], v[138:139] op_sel_hi:[1,0]
	v_pk_mul_f32 v[58:59], v[58:59], v[138:139] op_sel_hi:[1,0]
	v_pk_mul_f32 v[72:73], v[72:73], v[138:139] op_sel_hi:[1,0]
	v_pk_mul_f32 v[70:71], v[70:71], v[138:139] op_sel_hi:[1,0]
	v_pk_mul_f32 v[68:69], v[68:69], v[138:139] op_sel_hi:[1,0]
	v_pk_mul_f32 v[66:67], v[66:67], v[138:139] op_sel_hi:[1,0]
	v_pk_mul_f32 v[64:65], v[64:65], v[138:139] op_sel_hi:[1,0]
	v_pk_mul_f32 v[62:63], v[62:63], v[138:139] op_sel_hi:[1,0]
	v_mov_b32_e32 v138, v145
	s_branch .LBB0_569
